# attention: gather of sub-block sb+1 issued after the logits of sb (lands under softmax+PV), new destination quads
# baseline (speedup 1.0000x reference)
.LBB0_135:
	s_and_b32 s0, s76, 0x7ffff000
	s_mov_b32 s1, s77
	s_lshl_b64 s[0:1], s[0:1], 9
	v_mov_b32_e32 v72, 0
	s_and_b32 s29, s76, 0xfff
	v_mad_u64_u32 v[106:107], s[2:3], s76, v188, v[100:101]
	v_lshl_add_u64 v[108:109], v[102:103], 0, s[0:1]
	v_mov_b32_e32 v128, 0xff800000
	global_load_dwordx4 v[196:199], v[106:107], off
	global_load_dwordx4 v[200:203], v[106:107], off offset:64
	global_load_dwordx4 v[204:207], v[106:107], off offset:128
	global_load_dwordx4 v[208:211], v[106:107], off offset:192
	global_load_dwordx4 v[212:215], v[106:107], off offset:256
	global_load_dwordx4 v[216:219], v[106:107], off offset:320
	global_load_dwordx4 v[220:223], v[106:107], off offset:384
	global_load_dwordx4 v[224:227], v[106:107], off offset:448
	s_mov_b32 s30, 0
	v_mov_b32_e32 v68, 0
	v_mov_b32_e32 v69, v72
	v_mov_b32_e32 v70, v72
	v_mov_b32_e32 v71, v72
	v_mov_b32_e32 v24, 0
	v_mov_b32_e32 v25, v72
	v_mov_b32_e32 v26, v72
	v_mov_b32_e32 v27, v72
	v_mov_b32_e32 v64, 0
	v_mov_b32_e32 v65, v72
	v_mov_b32_e32 v66, v72
	v_mov_b32_e32 v67, v72
	v_mov_b32_e32 v60, 0
	v_mov_b32_e32 v61, v72
	v_mov_b32_e32 v62, v72
	v_mov_b32_e32 v63, v72
	v_mov_b32_e32 v56, 0
	v_mov_b32_e32 v57, v72
	v_mov_b32_e32 v58, v72
	v_mov_b32_e32 v59, v72
	v_mov_b32_e32 v52, 0
	v_mov_b32_e32 v53, v72
	v_mov_b32_e32 v54, v72
	v_mov_b32_e32 v55, v72
	v_mov_b32_e32 v48, 0
	v_mov_b32_e32 v49, v72
	v_mov_b32_e32 v50, v72
	v_mov_b32_e32 v51, v72
	v_mov_b32_e32 v44, 0
	v_mov_b32_e32 v45, v72
	v_mov_b32_e32 v46, v72
	v_mov_b32_e32 v47, v72
	v_mov_b32_e32 v40, 0
	v_mov_b32_e32 v41, v72
	v_mov_b32_e32 v42, v72
	v_mov_b32_e32 v43, v72
	v_mov_b32_e32 v28, 0
	v_mov_b32_e32 v29, v72
	v_mov_b32_e32 v30, v72
	v_mov_b32_e32 v31, v72
	v_mov_b32_e32 v20, 0
	v_mov_b32_e32 v21, v72
	v_mov_b32_e32 v22, v72
	v_mov_b32_e32 v23, v72
	v_mov_b32_e32 v16, 0
	v_mov_b32_e32 v17, v72
	v_mov_b32_e32 v18, v72
	v_mov_b32_e32 v19, v72
	v_mov_b32_e32 v12, 0
	v_mov_b32_e32 v13, v72
	v_mov_b32_e32 v14, v72
	v_mov_b32_e32 v15, v72
	v_mov_b32_e32 v8, 0
	v_mov_b32_e32 v9, v72
	v_mov_b32_e32 v10, v72
	v_mov_b32_e32 v11, v72
	v_mov_b32_e32 v4, 0
	v_mov_b32_e32 v5, v72
	v_mov_b32_e32 v6, v72
	v_mov_b32_e32 v7, v72
	v_mov_b32_e32 v0, 0
	v_mov_b32_e32 v1, v72
	v_mov_b32_e32 v2, v72
	v_mov_b32_e32 v3, v72
	v_mov_b32_e32 v244, v124
	v_lshlrev_b32_e32 v245, 2, v115
	ds_bpermute_b32 v88, v245, v244
	ds_bpermute_b32 v92, v245, v244 offset:8
	ds_bpermute_b32 v96, v245, v244 offset:16
	ds_bpermute_b32 v144, v245, v244 offset:24
	ds_bpermute_b32 v152, v245, v244 offset:32
	ds_bpermute_b32 v156, v245, v244 offset:40
	ds_bpermute_b32 v160, v245, v244 offset:48
	ds_bpermute_b32 v172, v245, v244 offset:56
	ds_bpermute_b32 v192, v245, v244 offset:64
	ds_bpermute_b32 v132, v245, v244 offset:72
	ds_bpermute_b32 v136, v245, v244 offset:80
	ds_bpermute_b32 v140, v245, v244 offset:88
	ds_bpermute_b32 v228, v245, v244 offset:96
	ds_bpermute_b32 v232, v245, v244 offset:104
	ds_bpermute_b32 v236, v245, v244 offset:112
	ds_bpermute_b32 v240, v245, v244 offset:120
	s_waitcnt lgkmcnt(15)
	v_max_i32_e32 v88, 0, v88
	v_lshlrev_b32_e32 v88, 8, v88
	v_mov_b32_e32 v89, v32
	v_lshl_add_u64 v[88:89], v[88:89], 1, v[108:109]
	global_load_dwordx4 v[88:91], v[88:89], off
	s_waitcnt lgkmcnt(14)
	v_max_i32_e32 v92, 0, v92
	v_lshlrev_b32_e32 v92, 8, v92
	v_mov_b32_e32 v93, v32
	v_lshl_add_u64 v[92:93], v[92:93], 1, v[108:109]
	global_load_dwordx4 v[92:95], v[92:93], off
	s_waitcnt lgkmcnt(13)
	v_max_i32_e32 v96, 0, v96
	v_lshlrev_b32_e32 v96, 8, v96
	v_mov_b32_e32 v97, v32
	v_lshl_add_u64 v[96:97], v[96:97], 1, v[108:109]
	global_load_dwordx4 v[96:99], v[96:97], off
	s_waitcnt lgkmcnt(12)
	v_max_i32_e32 v144, 0, v144
	v_lshlrev_b32_e32 v144, 8, v144
	v_mov_b32_e32 v145, v32
	v_lshl_add_u64 v[144:145], v[144:145], 1, v[108:109]
	global_load_dwordx4 v[144:147], v[144:145], off
	s_waitcnt lgkmcnt(11)
	v_max_i32_e32 v152, 0, v152
	v_lshlrev_b32_e32 v152, 8, v152
	v_mov_b32_e32 v153, v32
	v_lshl_add_u64 v[152:153], v[152:153], 1, v[108:109]
	global_load_dwordx4 v[152:155], v[152:153], off
	s_waitcnt lgkmcnt(10)
	v_max_i32_e32 v156, 0, v156
	v_lshlrev_b32_e32 v156, 8, v156
	v_mov_b32_e32 v157, v32
	v_lshl_add_u64 v[156:157], v[156:157], 1, v[108:109]
	global_load_dwordx4 v[156:159], v[156:157], off
	s_waitcnt lgkmcnt(9)
	v_max_i32_e32 v160, 0, v160
	v_lshlrev_b32_e32 v160, 8, v160
	v_mov_b32_e32 v161, v32
	v_lshl_add_u64 v[160:161], v[160:161], 1, v[108:109]
	global_load_dwordx4 v[160:163], v[160:161], off
	s_waitcnt lgkmcnt(8)
	v_max_i32_e32 v172, 0, v172
	v_lshlrev_b32_e32 v172, 8, v172
	v_mov_b32_e32 v173, v32
	v_lshl_add_u64 v[172:173], v[172:173], 1, v[108:109]
	global_load_dwordx4 v[172:175], v[172:173], off
	s_waitcnt lgkmcnt(7)
	v_max_i32_e32 v192, 0, v192
	v_lshlrev_b32_e32 v192, 8, v192
	v_mov_b32_e32 v193, v32
	v_lshl_add_u64 v[192:193], v[192:193], 1, v[108:109]
	global_load_dwordx4 v[192:195], v[192:193], off
	s_waitcnt lgkmcnt(6)
	v_max_i32_e32 v132, 0, v132
	v_lshlrev_b32_e32 v132, 8, v132
	v_mov_b32_e32 v133, v32
	v_lshl_add_u64 v[132:133], v[132:133], 1, v[108:109]
	global_load_dwordx4 v[132:135], v[132:133], off
	s_waitcnt lgkmcnt(5)
	v_max_i32_e32 v136, 0, v136
	v_lshlrev_b32_e32 v136, 8, v136
	v_mov_b32_e32 v137, v32
	v_lshl_add_u64 v[136:137], v[136:137], 1, v[108:109]
	global_load_dwordx4 v[136:139], v[136:137], off
	s_waitcnt lgkmcnt(4)
	v_max_i32_e32 v140, 0, v140
	v_lshlrev_b32_e32 v140, 8, v140
	v_mov_b32_e32 v141, v32
	v_lshl_add_u64 v[140:141], v[140:141], 1, v[108:109]
	global_load_dwordx4 v[140:143], v[140:141], off
	s_waitcnt lgkmcnt(3)
	v_max_i32_e32 v228, 0, v228
	v_lshlrev_b32_e32 v228, 8, v228
	v_mov_b32_e32 v229, v32
	v_lshl_add_u64 v[228:229], v[228:229], 1, v[108:109]
	global_load_dwordx4 v[228:231], v[228:229], off
	s_waitcnt lgkmcnt(2)
	v_max_i32_e32 v232, 0, v232
	v_lshlrev_b32_e32 v232, 8, v232
	v_mov_b32_e32 v233, v32
	v_lshl_add_u64 v[232:233], v[232:233], 1, v[108:109]
	global_load_dwordx4 v[232:235], v[232:233], off
	s_waitcnt lgkmcnt(1)
	v_max_i32_e32 v236, 0, v236
	v_lshlrev_b32_e32 v236, 8, v236
	v_mov_b32_e32 v237, v32
	v_lshl_add_u64 v[236:237], v[236:237], 1, v[108:109]
	global_load_dwordx4 v[236:239], v[236:237], off
	s_waitcnt lgkmcnt(0)
	v_max_i32_e32 v240, 0, v240
	v_lshlrev_b32_e32 v240, 8, v240
	v_mov_b32_e32 v241, v32
	v_lshl_add_u64 v[240:241], v[240:241], 1, v[108:109]
	global_load_dwordx4 v[240:243], v[240:241], off
.LBB0_136:
	s_lshr_b32 s2, s30, 1
	s_cmp_lt_u32 s30, 2
	s_cselect_b64 vcc, -1, 0
	s_cmp_eq_u32 s2, 1
	s_cselect_b64 s[0:1], -1, 0
	s_cmp_eq_u32 s2, 2
	s_cselect_b64 s[2:3], -1, 0
	v_mov_b32_e32 v129, v72
	v_cndmask_b32_e64 v72, v127, v126, s[2:3]
	v_cndmask_b32_e64 v72, v72, v125, s[0:1]
	s_and_b32 s0, s28, 32
	v_cndmask_b32_e32 v130, v72, v124, vcc
	s_waitcnt vmcnt(15)
	ds_write_b128 v117, v[88:91]
	s_waitcnt vmcnt(14)
	ds_write_b128 v117, v[92:95] offset:1056
	s_waitcnt vmcnt(13)
	ds_write_b128 v117, v[96:99] offset:2112
	s_waitcnt vmcnt(12)
	ds_write_b128 v117, v[144:147] offset:3168
	s_waitcnt vmcnt(11)
	ds_write_b128 v117, v[152:155] offset:4224
	s_waitcnt vmcnt(10)
	ds_write_b128 v117, v[156:159] offset:5280
	s_waitcnt vmcnt(9)
	ds_write_b128 v117, v[160:163] offset:6336
	s_waitcnt vmcnt(8)
	ds_write_b128 v117, v[172:175] offset:7392
	s_waitcnt vmcnt(7)
	ds_write_b128 v117, v[192:195] offset:8448
	s_waitcnt vmcnt(6)
	ds_write_b128 v117, v[132:135] offset:9504
	s_waitcnt vmcnt(5)
	ds_write_b128 v117, v[136:139] offset:10560
	s_waitcnt vmcnt(4)
	ds_write_b128 v117, v[140:143] offset:11616
	s_waitcnt vmcnt(3)
	ds_write_b128 v117, v[228:231] offset:12672
	s_waitcnt vmcnt(2)
	ds_write_b128 v117, v[232:235] offset:13728
	s_waitcnt vmcnt(1)
	ds_write_b128 v117, v[236:239] offset:14784
	s_waitcnt vmcnt(0)
	ds_write_b128 v117, v[240:243] offset:15840
	v_or_b32_e32 v72, s0, v33
	v_or_b32_e32 v73, v72, v180
	v_lshlrev_b32_e32 v73, 2, v73
	ds_bpermute_b32 v138, v73, v130
	v_or_b32_e32 v73, v72, v110
	v_lshlrev_b32_e32 v73, 2, v73
	ds_bpermute_b32 v139, v73, v130
	v_or_b32_e32 v73, v72, v111
	v_lshlrev_b32_e32 v73, 2, v73
	ds_bpermute_b32 v140, v73, v130
	v_or_b32_e32 v73, v72, v112
	v_lshlrev_b32_e32 v73, 2, v73
	v_or_b32_e32 v72, 16, v72
	ds_bpermute_b32 v141, v73, v130
	v_or_b32_e32 v73, v72, v180
	v_lshlrev_b32_e32 v73, 2, v73
	ds_bpermute_b32 v142, v73, v130
	v_or_b32_e32 v73, v72, v110
	v_lshlrev_b32_e32 v73, 2, v73
	ds_bpermute_b32 v143, v73, v130
	v_or_b32_e32 v73, v72, v111
	v_or_b32_e32 v72, v72, v112
	v_lshlrev_b32_e32 v73, 2, v73
	v_lshlrev_b32_e32 v72, 2, v72
	s_mov_b64 s[0:1], 0
	ds_bpermute_b32 v148, v73, v130
	ds_bpermute_b32 v149, v72, v130
	s_waitcnt lgkmcnt(7)
	v_cmp_lt_i32_e32 vcc, -1, v138
	s_waitcnt lgkmcnt(0)
	ds_read_b128 v[228:231], v118
	ds_read_b128 v[232:235], v118 offset:64
	ds_read_b128 v[236:239], v118 offset:128
	ds_read_b128 v[240:243], v118 offset:192
	s_waitcnt lgkmcnt(3)
	v_mfma_f32_16x16x32_bf16 v[134:137], v[228:231], v[196:199], 0
	ds_read_b128 v[228:231], v118 offset:256
	s_waitcnt lgkmcnt(3)
	v_mfma_f32_16x16x32_bf16 v[134:137], v[232:235], v[200:203], v[134:137]
	ds_read_b128 v[232:235], v118 offset:320
	s_waitcnt lgkmcnt(3)
	v_mfma_f32_16x16x32_bf16 v[134:137], v[236:239], v[204:207], v[134:137]
	ds_read_b128 v[236:239], v118 offset:384
	s_waitcnt lgkmcnt(3)
	v_mfma_f32_16x16x32_bf16 v[134:137], v[240:243], v[208:211], v[134:137]
	ds_read_b128 v[240:243], v118 offset:448
	s_waitcnt lgkmcnt(3)
	v_mfma_f32_16x16x32_bf16 v[134:137], v[228:231], v[212:215], v[134:137]
	ds_read_b128 v[228:231], v118 offset:8448
	s_waitcnt lgkmcnt(3)
	v_mfma_f32_16x16x32_bf16 v[134:137], v[232:235], v[216:219], v[134:137]
	ds_read_b128 v[232:235], v118 offset:8512
	s_waitcnt lgkmcnt(3)
	v_mfma_f32_16x16x32_bf16 v[134:137], v[236:239], v[220:223], v[134:137]
	ds_read_b128 v[236:239], v118 offset:8576
	s_waitcnt lgkmcnt(3)
	v_mfma_f32_16x16x32_bf16 v[134:137], v[240:243], v[224:227], v[134:137]
	ds_read_b128 v[240:243], v118 offset:8640
	s_waitcnt lgkmcnt(3)
	v_mfma_f32_16x16x32_bf16 v[72:75], v[228:231], v[196:199], 0
	ds_read_b128 v[228:231], v118 offset:8704
	s_waitcnt lgkmcnt(3)
	v_mfma_f32_16x16x32_bf16 v[72:75], v[232:235], v[200:203], v[72:75]
	ds_read_b128 v[232:235], v118 offset:8768
	s_waitcnt lgkmcnt(3)
	v_mfma_f32_16x16x32_bf16 v[72:75], v[236:239], v[204:207], v[72:75]
	ds_read_b128 v[236:239], v118 offset:8832
	s_waitcnt lgkmcnt(3)
	v_mfma_f32_16x16x32_bf16 v[72:75], v[240:243], v[208:211], v[72:75]
	ds_read_b128 v[240:243], v118 offset:8896
	v_subrev_u32_e32 v80, s29, v142
	v_med3_i32 v80, v80, s4, v189
	v_lshl_add_u32 v80, v80, 6, v116
	ds_read_b32 v80, v80 offset:8192
	s_waitcnt lgkmcnt(4)
	v_mfma_f32_16x16x32_bf16 v[72:75], v[228:231], v[212:215], v[72:75]
	s_waitcnt lgkmcnt(3)
	v_mfma_f32_16x16x32_bf16 v[72:75], v[232:235], v[216:219], v[72:75]
	s_waitcnt lgkmcnt(2)
	v_mfma_f32_16x16x32_bf16 v[72:75], v[236:239], v[220:223], v[72:75]
	s_waitcnt lgkmcnt(1)
	v_mfma_f32_16x16x32_bf16 v[72:75], v[240:243], v[224:227], v[72:75]
	v_subrev_u32_e32 v76, s29, v138
	v_med3_i32 v76, v76, s4, v189
	v_subrev_u32_e32 v77, s29, v139
	v_lshl_add_u32 v76, v76, 6, v116
	v_med3_i32 v77, v77, s4, v189
	v_subrev_u32_e32 v78, s29, v140
	ds_read_b32 v76, v76 offset:8192
	v_lshl_add_u32 v77, v77, 6, v116
	v_med3_i32 v78, v78, s4, v189
	v_subrev_u32_e32 v79, s29, v141
	ds_read_b32 v77, v77 offset:8192
	v_lshl_add_u32 v78, v78, 6, v116
	v_med3_i32 v79, v79, s4, v189
	ds_read_b32 v78, v78 offset:8192
	v_lshl_add_u32 v79, v79, 6, v116
	ds_read_b32 v79, v79 offset:8192
	s_waitcnt lgkmcnt(3)
	v_fmac_f32_e32 v76, 0x3d800000, v134
	v_cndmask_b32_e32 v76, v190, v76, vcc
	s_waitcnt lgkmcnt(2)
	v_fmac_f32_e32 v77, 0x3d800000, v135
	v_cmp_lt_i32_e32 vcc, -1, v139
	s_waitcnt lgkmcnt(1)
	v_fmac_f32_e32 v78, 0x3d800000, v136
	s_waitcnt lgkmcnt(0)
	v_fmac_f32_e32 v79, 0x3d800000, v137
	v_cndmask_b32_e32 v77, v190, v77, vcc
	v_cmp_lt_i32_e32 vcc, -1, v140
	v_fmac_f32_e32 v80, 0x3d800000, v72
	s_nop 0
	v_cndmask_b32_e32 v78, v190, v78, vcc
	v_cmp_lt_i32_e32 vcc, -1, v141
	s_nop 1
	v_cndmask_b32_e32 v79, v190, v79, vcc
	v_cmp_lt_i32_e32 vcc, -1, v142
	v_max_f32_e32 v81, v78, v79
	s_nop 0
	v_cndmask_b32_e32 v72, v190, v80, vcc
	v_subrev_u32_e32 v80, s29, v143
	v_med3_i32 v80, v80, s4, v189
	v_lshl_add_u32 v80, v80, 6, v116
	ds_read_b32 v80, v80 offset:8192
	v_cmp_lt_i32_e32 vcc, -1, v143
	s_waitcnt lgkmcnt(0)
	v_fmac_f32_e32 v80, 0x3d800000, v73
	v_subrev_u32_e32 v73, s29, v148
	v_med3_i32 v73, v73, s4, v189
	v_lshl_add_u32 v73, v73, 6, v116
	ds_read_b32 v73, v73 offset:8192
	v_cndmask_b32_e32 v80, v190, v80, vcc
	v_cmp_lt_i32_e32 vcc, -1, v148
	s_waitcnt lgkmcnt(0)
	v_fmac_f32_e32 v73, 0x3d800000, v74
	v_cndmask_b32_e32 v74, v190, v73, vcc
	v_subrev_u32_e32 v73, s29, v149
	v_med3_i32 v73, v73, s4, v189
	v_lshl_add_u32 v73, v73, 6, v116
	ds_read_b32 v73, v73 offset:8192
	v_cmp_lt_i32_e32 vcc, -1, v149
	s_waitcnt lgkmcnt(0)
	v_fmac_f32_e32 v73, 0x3d800000, v75
	v_cndmask_b32_e32 v75, v190, v73, vcc
	s_add_i32 s2, s30, 1
	s_cmp_eq_u32 s2, 8
	s_cbranch_scc1 .Latt_nopf
	s_lshr_b32 s3, s2, 1
	s_cmp_eq_u32 s3, 2
	s_cselect_b64 vcc, -1, 0
	v_cndmask_b32_e32 v244, v127, v126, vcc
	s_cmp_eq_u32 s3, 1
	s_cselect_b64 vcc, -1, 0
	v_cndmask_b32_e32 v244, v244, v125, vcc
	s_cmp_eq_u32 s3, 0
	s_cselect_b64 vcc, -1, 0
	v_cndmask_b32_e32 v244, v244, v124, vcc
	s_add_i32 s3, s28, 32
	s_and_b32 s3, s3, 32
	v_or_b32_e32 v245, s3, v115
	v_lshlrev_b32_e32 v245, 2, v245
	ds_bpermute_b32 v88, v245, v244
	ds_bpermute_b32 v92, v245, v244 offset:8
	ds_bpermute_b32 v96, v245, v244 offset:16
	ds_bpermute_b32 v144, v245, v244 offset:24
	ds_bpermute_b32 v152, v245, v244 offset:32
	ds_bpermute_b32 v156, v245, v244 offset:40
	ds_bpermute_b32 v160, v245, v244 offset:48
	ds_bpermute_b32 v172, v245, v244 offset:56
	ds_bpermute_b32 v192, v245, v244 offset:64
	ds_bpermute_b32 v132, v245, v244 offset:72
	ds_bpermute_b32 v136, v245, v244 offset:80
	ds_bpermute_b32 v140, v245, v244 offset:88
	ds_bpermute_b32 v228, v245, v244 offset:96
	ds_bpermute_b32 v232, v245, v244 offset:104
	ds_bpermute_b32 v236, v245, v244 offset:112
	ds_bpermute_b32 v240, v245, v244 offset:120
	s_waitcnt lgkmcnt(15)
	v_max_i32_e32 v88, 0, v88
	v_lshlrev_b32_e32 v88, 8, v88
	v_mov_b32_e32 v89, v32
	v_lshl_add_u64 v[88:89], v[88:89], 1, v[108:109]
	global_load_dwordx4 v[88:91], v[88:89], off
	s_waitcnt lgkmcnt(14)
	v_max_i32_e32 v92, 0, v92
	v_lshlrev_b32_e32 v92, 8, v92
	v_mov_b32_e32 v93, v32
	v_lshl_add_u64 v[92:93], v[92:93], 1, v[108:109]
	global_load_dwordx4 v[92:95], v[92:93], off
	s_waitcnt lgkmcnt(13)
	v_max_i32_e32 v96, 0, v96
	v_lshlrev_b32_e32 v96, 8, v96
	v_mov_b32_e32 v97, v32
	v_lshl_add_u64 v[96:97], v[96:97], 1, v[108:109]
	global_load_dwordx4 v[96:99], v[96:97], off
	s_waitcnt lgkmcnt(12)
	v_max_i32_e32 v144, 0, v144
	v_lshlrev_b32_e32 v144, 8, v144
	v_mov_b32_e32 v145, v32
	v_lshl_add_u64 v[144:145], v[144:145], 1, v[108:109]
	global_load_dwordx4 v[144:147], v[144:145], off
	s_waitcnt lgkmcnt(11)
	v_max_i32_e32 v152, 0, v152
	v_lshlrev_b32_e32 v152, 8, v152
	v_mov_b32_e32 v153, v32
	v_lshl_add_u64 v[152:153], v[152:153], 1, v[108:109]
	global_load_dwordx4 v[152:155], v[152:153], off
	s_waitcnt lgkmcnt(10)
	v_max_i32_e32 v156, 0, v156
	v_lshlrev_b32_e32 v156, 8, v156
	v_mov_b32_e32 v157, v32
	v_lshl_add_u64 v[156:157], v[156:157], 1, v[108:109]
	global_load_dwordx4 v[156:159], v[156:157], off
	s_waitcnt lgkmcnt(9)
	v_max_i32_e32 v160, 0, v160
	v_lshlrev_b32_e32 v160, 8, v160
	v_mov_b32_e32 v161, v32
	v_lshl_add_u64 v[160:161], v[160:161], 1, v[108:109]
	global_load_dwordx4 v[160:163], v[160:161], off
	s_waitcnt lgkmcnt(8)
	v_max_i32_e32 v172, 0, v172
	v_lshlrev_b32_e32 v172, 8, v172
	v_mov_b32_e32 v173, v32
	v_lshl_add_u64 v[172:173], v[172:173], 1, v[108:109]
	global_load_dwordx4 v[172:175], v[172:173], off
	s_waitcnt lgkmcnt(7)
	v_max_i32_e32 v192, 0, v192
	v_lshlrev_b32_e32 v192, 8, v192
	v_mov_b32_e32 v193, v32
	v_lshl_add_u64 v[192:193], v[192:193], 1, v[108:109]
	global_load_dwordx4 v[192:195], v[192:193], off
	s_waitcnt lgkmcnt(6)
	v_max_i32_e32 v132, 0, v132
	v_lshlrev_b32_e32 v132, 8, v132
	v_mov_b32_e32 v133, v32
	v_lshl_add_u64 v[132:133], v[132:133], 1, v[108:109]
	global_load_dwordx4 v[132:135], v[132:133], off
	s_waitcnt lgkmcnt(5)
	v_max_i32_e32 v136, 0, v136
	v_lshlrev_b32_e32 v136, 8, v136
	v_mov_b32_e32 v137, v32
	v_lshl_add_u64 v[136:137], v[136:137], 1, v[108:109]
	global_load_dwordx4 v[136:139], v[136:137], off
	s_waitcnt lgkmcnt(4)
	v_max_i32_e32 v140, 0, v140
	v_lshlrev_b32_e32 v140, 8, v140
	v_mov_b32_e32 v141, v32
	v_lshl_add_u64 v[140:141], v[140:141], 1, v[108:109]
	global_load_dwordx4 v[140:143], v[140:141], off
	s_waitcnt lgkmcnt(3)
	v_max_i32_e32 v228, 0, v228
	v_lshlrev_b32_e32 v228, 8, v228
	v_mov_b32_e32 v229, v32
	v_lshl_add_u64 v[228:229], v[228:229], 1, v[108:109]
	global_load_dwordx4 v[228:231], v[228:229], off
	s_waitcnt lgkmcnt(2)
	v_max_i32_e32 v232, 0, v232
	v_lshlrev_b32_e32 v232, 8, v232
	v_mov_b32_e32 v233, v32
	v_lshl_add_u64 v[232:233], v[232:233], 1, v[108:109]
	global_load_dwordx4 v[232:235], v[232:233], off
	s_waitcnt lgkmcnt(1)
	v_max_i32_e32 v236, 0, v236
	v_lshlrev_b32_e32 v236, 8, v236
	v_mov_b32_e32 v237, v32
	v_lshl_add_u64 v[236:237], v[236:237], 1, v[108:109]
	global_load_dwordx4 v[236:239], v[236:237], off
	s_waitcnt lgkmcnt(0)
	v_max_i32_e32 v240, 0, v240
	v_lshlrev_b32_e32 v240, 8, v240
	v_mov_b32_e32 v241, v32
	v_lshl_add_u64 v[240:241], v[240:241], 1, v[108:109]
	global_load_dwordx4 v[240:243], v[240:241], off
.Latt_nopf:
	v_max_f32_e32 v82, v74, v75
	v_max_f32_e32 v73, v76, v77
	v_max3_f32 v82, v72, v80, v82
	v_max3_f32 v73, v73, v81, v82
	ds_bpermute_b32 v81, v113, v73
	s_waitcnt lgkmcnt(0)
	v_max_f32_e32 v81, v81, v81
	v_max_f32_e32 v73, v73, v81
	ds_bpermute_b32 v81, v114, v73
	s_waitcnt lgkmcnt(0)
	v_max3_f32 v73, v128, v73, v81
	v_sub_f32_e32 v72, v72, v73
	v_mul_f32_e32 v72, 0x3fb8aa3b, v72
	v_sub_f32_e32 v76, v76, v73
	v_exp_f32_e32 v82, v72
	v_sub_f32_e32 v72, v80, v73
	v_mul_f32_e32 v76, 0x3fb8aa3b, v76
	v_sub_f32_e32 v77, v77, v73
	v_mul_f32_e32 v72, 0x3fb8aa3b, v72
	v_exp_f32_e32 v76, v76
	v_mul_f32_e32 v77, 0x3fb8aa3b, v77
	v_sub_f32_e32 v78, v78, v73
	v_exp_f32_e32 v80, v72
	v_sub_f32_e32 v72, v74, v73
	v_exp_f32_e32 v77, v77
	v_mul_f32_e32 v78, 0x3fb8aa3b, v78
	v_sub_f32_e32 v79, v79, v73
	v_mul_f32_e32 v72, 0x3fb8aa3b, v72
	v_exp_f32_e32 v78, v78
	v_mul_f32_e32 v79, 0x3fb8aa3b, v79
	v_exp_f32_e32 v83, v72
	v_sub_f32_e32 v72, v75, v73
	v_exp_f32_e32 v79, v79
	v_mul_f32_e32 v72, 0x3fb8aa3b, v72
	v_exp_f32_e32 v84, v72
	v_add_f32_e32 v72, 0, v76
	v_add_f32_e32 v72, v77, v72
	v_add_f32_e32 v72, v78, v72
	v_sub_f32_e32 v81, v128, v73
	v_add_f32_e32 v72, v79, v72
	v_mul_f32_e32 v81, 0x3fb8aa3b, v81
	v_add_f32_e32 v72, v82, v72
	v_exp_f32_e32 v86, v81
	v_add_f32_e32 v72, v80, v72
	v_add_f32_e32 v72, v83, v72
	v_cvt_pk_bf16_f32 v74, v76, v77
	v_cvt_pk_bf16_f32 v75, v78, v79
	v_cvt_pk_bf16_f32 v76, v82, v80
	v_cvt_pk_bf16_f32 v77, v83, v84
	ds_read_b64_tr_b16 v[80:81], v119 offset:8448
	ds_read_b64_tr_b16 v[78:79], v119
	ds_read_b64_tr_b16 v[82:83], v119 offset:32
	v_pk_mul_f32 v[70:71], v[70:71], v[86:87] op_sel_hi:[1,0]
	v_pk_mul_f32 v[68:69], v[68:69], v[86:87] op_sel_hi:[1,0]
	v_add_f32_e32 v72, v84, v72
	ds_read_b64_tr_b16 v[84:85], v119 offset:8480
	s_waitcnt lgkmcnt(2)
	v_mfma_f32_16x16x32_bf16 v[68:71], v[78:81], v[74:77], v[68:71]
	ds_read_b64_tr_b16 v[78:79], v119 offset:64
	ds_read_b64_tr_b16 v[80:81], v119 offset:8512
	v_pk_mul_f32 v[66:67], v[66:67], v[86:87] op_sel_hi:[1,0]
	v_pk_mul_f32 v[64:65], v[64:65], v[86:87] op_sel_hi:[1,0]
	v_pk_mul_f32 v[62:63], v[62:63], v[86:87] op_sel_hi:[1,0]
	v_pk_mul_f32 v[60:61], v[60:61], v[86:87] op_sel_hi:[1,0]
	s_waitcnt lgkmcnt(0)
	v_mfma_f32_16x16x32_bf16 v[64:67], v[78:81], v[74:77], v[64:67]
	ds_read_b64_tr_b16 v[78:79], v119 offset:96
	ds_read_b64_tr_b16 v[80:81], v119 offset:8544
	v_pk_mul_f32 v[26:27], v[26:27], v[86:87] op_sel_hi:[1,0]
	v_pk_mul_f32 v[24:25], v[24:25], v[86:87] op_sel_hi:[1,0]
	s_waitcnt lgkmcnt(0)
	v_mfma_f32_16x16x32_bf16 v[60:63], v[78:81], v[74:77], v[60:63]
	v_mul_f32_e64 v58, v58, v86
	v_mul_f32_e64 v59, v59, v86
	v_pk_mul_f32 v[56:57], v[56:57], v[86:87] op_sel_hi:[1,0]
	v_pk_mul_f32 v[50:51], v[50:51], v[86:87] op_sel_hi:[1,0]
	v_mfma_f32_16x16x32_bf16 v[24:27], v[82:85], v[74:77], v[24:27]
	ds_read_b64_tr_b16 v[80:81], v119 offset:8576
	ds_read_b64_tr_b16 v[78:79], v119 offset:128
	ds_read_b64_tr_b16 v[82:83], v119 offset:160
	ds_read_b64_tr_b16 v[84:85], v119 offset:8608
	v_pk_mul_f32 v[48:49], v[48:49], v[86:87] op_sel_hi:[1,0]
	s_waitcnt lgkmcnt(2)
	v_mfma_f32_16x16x32_bf16 v[56:59], v[78:81], v[74:77], v[56:59]
	ds_read_b64_tr_b16 v[78:79], v119 offset:192
	ds_read_b64_tr_b16 v[80:81], v119 offset:8640
	v_pk_mul_f32 v[54:55], v[54:55], v[86:87] op_sel_hi:[1,0]
	v_pk_mul_f32 v[52:53], v[52:53], v[86:87] op_sel_hi:[1,0]
	s_waitcnt lgkmcnt(0)
	v_mfma_f32_16x16x32_bf16 v[48:51], v[78:81], v[74:77], v[48:51]
	ds_read_b64_tr_b16 v[78:79], v119 offset:224
	ds_read_b64_tr_b16 v[80:81], v119 offset:8672
	v_pk_mul_f32 v[46:47], v[46:47], v[86:87] op_sel_hi:[1,0]
	v_pk_mul_f32 v[44:45], v[44:45], v[86:87] op_sel_hi:[1,0]
	v_mfma_f32_16x16x32_bf16 v[52:55], v[82:85], v[74:77], v[52:55]
	v_mul_f32_e64 v42, v42, v86
	v_mul_f32_e64 v43, v43, v86
	v_pk_mul_f32 v[40:41], v[40:41], v[86:87] op_sel_hi:[1,0]
	v_pk_mul_f32 v[22:23], v[22:23], v[86:87] op_sel_hi:[1,0]
	s_waitcnt lgkmcnt(0)
	v_mfma_f32_16x16x32_bf16 v[44:47], v[78:81], v[74:77], v[44:47]
	ds_read_b64_tr_b16 v[80:81], v119 offset:8704
	ds_read_b64_tr_b16 v[78:79], v119 offset:256
	ds_read_b64_tr_b16 v[82:83], v119 offset:288
	ds_read_b64_tr_b16 v[84:85], v119 offset:8736
	v_pk_mul_f32 v[20:21], v[20:21], v[86:87] op_sel_hi:[1,0]
	s_waitcnt lgkmcnt(2)
	v_mfma_f32_16x16x32_bf16 v[40:43], v[78:81], v[74:77], v[40:43]
	ds_read_b64_tr_b16 v[78:79], v119 offset:320
	ds_read_b64_tr_b16 v[80:81], v119 offset:8768
	v_pk_mul_f32 v[30:31], v[30:31], v[86:87] op_sel_hi:[1,0]
	v_pk_mul_f32 v[28:29], v[28:29], v[86:87] op_sel_hi:[1,0]
	s_waitcnt lgkmcnt(0)
	v_mfma_f32_16x16x32_bf16 v[20:23], v[78:81], v[74:77], v[20:23]
	ds_read_b64_tr_b16 v[78:79], v119 offset:352
	ds_read_b64_tr_b16 v[80:81], v119 offset:8800
	v_pk_mul_f32 v[18:19], v[18:19], v[86:87] op_sel_hi:[1,0]
	v_pk_mul_f32 v[16:17], v[16:17], v[86:87] op_sel_hi:[1,0]
	v_mfma_f32_16x16x32_bf16 v[28:31], v[82:85], v[74:77], v[28:31]
	v_mul_f32_e64 v14, v14, v86
	v_mul_f32_e64 v15, v15, v86
	v_pk_mul_f32 v[12:13], v[12:13], v[86:87] op_sel_hi:[1,0]
	v_pk_mul_f32 v[6:7], v[6:7], v[86:87] op_sel_hi:[1,0]
	s_waitcnt lgkmcnt(0)
	v_mfma_f32_16x16x32_bf16 v[16:19], v[78:81], v[74:77], v[16:19]
	ds_read_b64_tr_b16 v[80:81], v119 offset:8832
	ds_read_b64_tr_b16 v[78:79], v119 offset:384
	ds_read_b64_tr_b16 v[82:83], v119 offset:416
	ds_read_b64_tr_b16 v[84:85], v119 offset:8864
	v_pk_mul_f32 v[4:5], v[4:5], v[86:87] op_sel_hi:[1,0]
	s_waitcnt lgkmcnt(2)
	v_mfma_f32_16x16x32_bf16 v[12:15], v[78:81], v[74:77], v[12:15]
	ds_read_b64_tr_b16 v[78:79], v119 offset:448
	ds_read_b64_tr_b16 v[80:81], v119 offset:8896
	v_pk_mul_f32 v[10:11], v[10:11], v[86:87] op_sel_hi:[1,0]
	v_pk_mul_f32 v[8:9], v[8:9], v[86:87] op_sel_hi:[1,0]
	s_waitcnt lgkmcnt(0)
	v_mfma_f32_16x16x32_bf16 v[4:7], v[78:81], v[74:77], v[4:7]
	ds_read_b64_tr_b16 v[78:79], v119 offset:480
	ds_read_b64_tr_b16 v[80:81], v119 offset:8928
	v_pk_mul_f32 v[2:3], v[2:3], v[86:87] op_sel_hi:[1,0]
	v_pk_mul_f32 v[0:1], v[0:1], v[86:87] op_sel_hi:[1,0]
	v_mfma_f32_16x16x32_bf16 v[8:11], v[82:85], v[74:77], v[8:11]
	s_waitcnt lgkmcnt(0)
	v_fmac_f32_e32 v72, v129, v86
	s_waitcnt lgkmcnt(0)
	v_mfma_f32_16x16x32_bf16 v[0:3], v[78:81], v[74:77], v[0:3]
	v_mov_b32_e32 v128, v73
	s_add_i32 s30, s30, 1
	s_add_i32 s28, s28, 32
	s_cmp_eq_u32 s30, 8
	s_cbranch_scc0 .LBB0_136
	ds_bpermute_b32 v73, v113, v72
	v_mov_b32_e32 v124, v123
	v_mov_b32_e32 v125, v122
	v_mov_b32_e32 v126, v121
	v_mov_b32_e32 v127, v120
	s_waitcnt lgkmcnt(0)
	v_add_f32_e32 v72, v72, v73
	ds_bpermute_b32 v73, v114, v72
	s_mov_b32 s2, s25
	s_waitcnt lgkmcnt(0)
	v_add_f32_e32 v72, v72, v73
	v_div_scale_f32 v73, s[0:1], v72, v72, 1.0
	v_rcp_f32_e32 v74, v73
	s_lshl_b64 s[0:1], s[76:77], 13
	s_mov_b32 s76, s38
	v_fma_f32 v75, -v73, v74, 1.0
	v_fmac_f32_e32 v74, v75, v74
	v_div_scale_f32 v75, vcc, 1.0, v72, 1.0
	v_mul_f32_e32 v76, v75, v74
	v_fma_f32 v77, -v73, v76, v75
	v_fmac_f32_e32 v76, v77, v74
	v_fma_f32 v73, -v73, v76, v75
	v_div_fmas_f32 v73, v73, v74, v76
	v_div_fixup_f32 v72, v73, v72, 1.0
	v_pk_mul_f32 v[24:25], v[24:25], v[72:73] op_sel_hi:[1,0]
	v_pk_mul_f32 v[26:27], v[26:27], v[72:73] op_sel_hi:[1,0]
	v_lshl_add_u64 v[74:75], v[104:105], 0, s[0:1]
	v_cvt_pk_bf16_f32 v24, v24, v25
	v_cvt_pk_bf16_f32 v25, v26, v27
	global_store_dwordx2 v[74:75], v[24:25], off offset:32
	v_pk_mul_f32 v[24:25], v[64:65], v[72:73] op_sel_hi:[1,0]
	v_pk_mul_f32 v[26:27], v[66:67], v[72:73] op_sel_hi:[1,0]
	v_cvt_pk_bf16_f32 v24, v24, v25
	v_cvt_pk_bf16_f32 v25, v26, v27
	global_store_dwordx2 v[74:75], v[24:25], off offset:64
	v_pk_mul_f32 v[24:25], v[60:61], v[72:73] op_sel_hi:[1,0]
	v_pk_mul_f32 v[26:27], v[62:63], v[72:73] op_sel_hi:[1,0]
	v_cvt_pk_bf16_f32 v24, v24, v25
	v_cvt_pk_bf16_f32 v25, v26, v27
	global_store_dwordx2 v[74:75], v[24:25], off offset:96
	v_pk_mul_f32 v[24:25], v[56:57], v[72:73] op_sel_hi:[1,0]
	v_pk_mul_f32 v[26:27], v[58:59], v[72:73] op_sel_hi:[1,0]
	v_cvt_pk_bf16_f32 v24, v24, v25
	v_cvt_pk_bf16_f32 v25, v26, v27
	global_store_dwordx2 v[74:75], v[24:25], off offset:128
	v_pk_mul_f32 v[24:25], v[52:53], v[72:73] op_sel_hi:[1,0]
	v_pk_mul_f32 v[26:27], v[54:55], v[72:73] op_sel_hi:[1,0]
	v_cvt_pk_bf16_f32 v24, v24, v25
	v_cvt_pk_bf16_f32 v25, v26, v27
	global_store_dwordx2 v[74:75], v[24:25], off offset:160
	v_pk_mul_f32 v[24:25], v[48:49], v[72:73] op_sel_hi:[1,0]
	v_pk_mul_f32 v[26:27], v[50:51], v[72:73] op_sel_hi:[1,0]
	v_cvt_pk_bf16_f32 v24, v24, v25
	v_cvt_pk_bf16_f32 v25, v26, v27
	global_store_dwordx2 v[74:75], v[24:25], off offset:192
	v_pk_mul_f32 v[24:25], v[44:45], v[72:73] op_sel_hi:[1,0]
	v_pk_mul_f32 v[26:27], v[46:47], v[72:73] op_sel_hi:[1,0]
	v_cvt_pk_bf16_f32 v24, v24, v25
	v_cvt_pk_bf16_f32 v25, v26, v27
	global_store_dwordx2 v[74:75], v[24:25], off offset:224
	v_pk_mul_f32 v[24:25], v[40:41], v[72:73] op_sel_hi:[1,0]
	v_pk_mul_f32 v[26:27], v[42:43], v[72:73] op_sel_hi:[1,0]
	v_cvt_pk_bf16_f32 v24, v24, v25
	v_cvt_pk_bf16_f32 v25, v26, v27
	v_pk_mul_f32 v[68:69], v[68:69], v[72:73] op_sel_hi:[1,0]
	v_pk_mul_f32 v[70:71], v[70:71], v[72:73] op_sel_hi:[1,0]
	global_store_dwordx2 v[74:75], v[24:25], off offset:256
	v_pk_mul_f32 v[24:25], v[28:29], v[72:73] op_sel_hi:[1,0]
	v_pk_mul_f32 v[26:27], v[30:31], v[72:73] op_sel_hi:[1,0]
	v_pk_mul_f32 v[20:21], v[20:21], v[72:73] op_sel_hi:[1,0]
	v_pk_mul_f32 v[22:23], v[22:23], v[72:73] op_sel_hi:[1,0]
	v_pk_mul_f32 v[16:17], v[16:17], v[72:73] op_sel_hi:[1,0]
	v_pk_mul_f32 v[18:19], v[18:19], v[72:73] op_sel_hi:[1,0]
	v_pk_mul_f32 v[12:13], v[12:13], v[72:73] op_sel_hi:[1,0]
	v_pk_mul_f32 v[14:15], v[14:15], v[72:73] op_sel_hi:[1,0]
	v_pk_mul_f32 v[8:9], v[8:9], v[72:73] op_sel_hi:[1,0]
	v_pk_mul_f32 v[10:11], v[10:11], v[72:73] op_sel_hi:[1,0]
	v_pk_mul_f32 v[4:5], v[4:5], v[72:73] op_sel_hi:[1,0]
	v_pk_mul_f32 v[6:7], v[6:7], v[72:73] op_sel_hi:[1,0]
	v_pk_mul_f32 v[0:1], v[0:1], v[72:73] op_sel_hi:[1,0]
	v_pk_mul_f32 v[2:3], v[2:3], v[72:73] op_sel_hi:[1,0]
	v_cvt_pk_bf16_f32 v68, v68, v69
	v_cvt_pk_bf16_f32 v69, v70, v71
	v_cvt_pk_bf16_f32 v24, v24, v25
	v_cvt_pk_bf16_f32 v25, v26, v27
	v_cvt_pk_bf16_f32 v20, v20, v21
	v_cvt_pk_bf16_f32 v21, v22, v23
	v_cvt_pk_bf16_f32 v16, v16, v17
	v_cvt_pk_bf16_f32 v17, v18, v19
	v_cvt_pk_bf16_f32 v12, v12, v13
	v_cvt_pk_bf16_f32 v13, v14, v15
	v_cvt_pk_bf16_f32 v8, v8, v9
	v_cvt_pk_bf16_f32 v9, v10, v11
	v_cvt_pk_bf16_f32 v4, v4, v5
	v_cvt_pk_bf16_f32 v5, v6, v7
	v_cvt_pk_bf16_f32 v0, v0, v1
	v_cvt_pk_bf16_f32 v1, v2, v3
	s_and_b64 vcc, exec, s[40:41]
	global_store_dwordx2 v[74:75], v[68:69], off
	global_store_dwordx2 v[74:75], v[24:25], off offset:288
	global_store_dwordx2 v[74:75], v[20:21], off offset:320
	global_store_dwordx2 v[74:75], v[16:17], off offset:352
	global_store_dwordx2 v[74:75], v[12:13], off offset:384
	global_store_dwordx2 v[74:75], v[8:9], off offset:416
	global_store_dwordx2 v[74:75], v[4:5], off offset:448
	global_store_dwordx2 v[74:75], v[0:1], off offset:480
	s_cbranch_vccz .LBB0_128
